# XCD-local grid barriers after the FFN wi and wo GEMM phases (leader skips L2 writeback + cross-XCD rendezvous when a runtime census shows every blockIdx%8 group sits on one XCC; global fallback otherw
# speedup vs baseline: 1.0230x; 1.0068x over previous
.LBB0_2:
	v_lshl_add_u32 v1, v0, 2, 0
	v_add_u32_e32 v1, 0x20000, v1
	v_mov_b32_e32 v2, 0
	ds_write2st64_b32 v1, v2, v2 offset1:8
	ds_write2st64_b32 v1, v2, v2 offset0:16 offset1:24
	v_or_b32_e32 v1, 0x800, v0
	s_mov_b64 s[0:1], -1
	s_and_saveexec_b64 s[4:5], s[0:1]
	v_lshl_add_u32 v3, v1, 2, 0
	v_add_u32_e32 v3, 0x20000, v3
	ds_write_b32 v3, v2
	s_or_b64 exec, exec, s[4:5]
	s_and_saveexec_b64 s[4:5], s[0:1]
	s_add_i32 s0, 0, 0x20000
	v_lshl_add_u32 v1, v1, 2, s0
	v_mov_b32_e32 v2, 0
	ds_write_b32 v1, v2 offset:2048
	s_or_b64 exec, exec, s[4:5]
	s_load_dwordx2 s[90:91], s[86:87], 0x198
	v_or_b32_e32 v1, 0xc00, v0
	v_cmp_gt_u32_e64 s[0:1], 7, 6
	v_cmp_gt_u32_e64 s[6:7], 7, 5
	s_and_saveexec_b64 s[4:5], s[6:7]
	v_lshl_add_u32 v2, v1, 2, 0
	v_add_u32_e32 v2, 0x20000, v2
	v_mov_b32_e32 v3, 0
	ds_write_b32 v2, v3
	s_or_b64 exec, exec, s[4:5]
	s_and_saveexec_b64 s[4:5], s[0:1]
	s_add_i32 s0, 0, 0x20000
	v_lshl_add_u32 v1, v1, 2, s0
	v_mov_b32_e32 v2, 0
	ds_write_b32 v1, v2 offset:2048
	s_or_b64 exec, exec, s[4:5]
	s_waitcnt lgkmcnt(0)
	s_barrier
	s_load_dwordx2 s[84:85], s[86:87], 0x1a0
	s_add_u32 s0, s90, 0x4000
	s_addc_u32 s1, s91, 0
	s_mov_b32 s3, 0
	v_cmp_eq_u32_e32 vcc, 0, v0
	s_waitcnt lgkmcnt(0)
	s_sub_i32 s4, s85, s84
	s_cmp_lt_i32 s4, 2
	s_mov_b32 s82, 0
	s_cbranch_scc1 .LBB0_15
	s_getreg_b32 s3, hwreg(HW_REG_XCC_ID, 0, 4)
	s_and_b32 s3, s3, 15
	s_and_saveexec_b64 s[4:5], vcc
	s_cbranch_execz .LBB0_14
	s_mov_b64 s[6:7], exec
	v_mbcnt_lo_u32_b32 v1, s6, 0
	v_mbcnt_hi_u32_b32 v1, s7, v1
	v_cmp_eq_u32_e32 vcc, 0, v1
	s_and_b64 s[10:11], exec, vcc
	s_mov_b64 exec, s[10:11]
	s_cbranch_execz .LBB0_14
	s_and_b32 s10, s2, 7
	s_lshl_b32 s10, s10, 8
	s_add_u32 s10, s10, 0x4000
	s_lshl_b32 s11, 1, s3
	v_mov_b32_e32 v3, s10
	v_mov_b32_e32 v4, s11
	global_atomic_or v4, v3, v4, s[0:1] sc0
	s_waitcnt vmcnt(0)
	s_lshl_b32 s9, s3, 8
	s_bcnt1_i32_b64 s6, s[6:7]
	v_mov_b32_e32 v1, s9
	v_mov_b32_e32 v2, s6
	global_atomic_add v1, v2, s[0:1] offset:1024

.LBB0_94:
	s_cmp_eq_u32 s3, 0
	s_cselect_b64 vcc, -1, 0
	s_cmp_eq_u32 s3, 1
	v_cndmask_b32_e32 v17, 0, v16, vcc
	s_cselect_b64 vcc, -1, 0
	s_cmp_eq_u32 s3, 2
	v_cndmask_b32_e32 v17, v17, v1, vcc
	s_cselect_b64 vcc, -1, 0
	s_cmp_eq_u32 s3, 3
	v_cndmask_b32_e32 v17, v17, v2, vcc
	s_cselect_b64 vcc, -1, 0
	s_cmp_eq_u32 s3, 4
	v_cndmask_b32_e32 v17, v17, v3, vcc
	s_cselect_b64 vcc, -1, 0
	s_cmp_eq_u32 s3, 5
	v_cndmask_b32_e32 v17, v17, v4, vcc
	s_cselect_b64 vcc, -1, 0
	s_cmp_eq_u32 s3, 6
	v_cndmask_b32_e32 v17, v17, v5, vcc
	s_cselect_b64 vcc, -1, 0
	s_cmp_eq_u32 s3, 7
	v_cndmask_b32_e32 v17, v17, v6, vcc
	s_cselect_b64 vcc, -1, 0
	s_cmp_eq_u32 s3, 8
	v_cndmask_b32_e32 v17, v17, v7, vcc
	s_cselect_b64 vcc, -1, 0
	s_cmp_eq_u32 s3, 9
	v_cndmask_b32_e32 v17, v17, v8, vcc
	s_cselect_b64 vcc, -1, 0
	s_cmp_eq_u32 s3, 10
	v_cndmask_b32_e32 v17, v17, v9, vcc
	s_cselect_b64 vcc, -1, 0
	s_cmp_eq_u32 s3, 11
	v_cndmask_b32_e32 v17, v17, v10, vcc
	s_cselect_b64 vcc, -1, 0
	s_cmp_eq_u32 s3, 12
	v_cndmask_b32_e32 v17, v17, v11, vcc
	s_cselect_b64 vcc, -1, 0
	s_cmp_eq_u32 s3, 13
	v_cndmask_b32_e32 v17, v17, v12, vcc
	s_cselect_b64 vcc, -1, 0
	s_cmp_eq_u32 s3, 14
	v_cndmask_b32_e32 v17, v17, v13, vcc
	s_cselect_b64 vcc, -1, 0
	s_cmp_eq_u32 s3, 15
	v_cndmask_b32_e32 v17, v17, v14, vcc
	s_cselect_b64 vcc, -1, 0
	v_cndmask_b32_e32 v17, v17, v15, vcc
	v_cmp_ne_u32_e32 vcc, 0, v16
	s_nop 1
	v_cndmask_b32_e64 v16, 0, 1, vcc
	v_cmp_ne_u32_e32 vcc, 0, v1
	s_nop 1
	v_addc_co_u32_e32 v1, vcc, 0, v16, vcc
	v_cmp_ne_u32_e32 vcc, 0, v2
	s_nop 1
	v_cndmask_b32_e64 v2, 0, 1, vcc
	v_cmp_ne_u32_e32 vcc, 0, v3
	v_max_u32_e32 v3, 1, v17
	s_nop 0
	v_addc_co_u32_e32 v1, vcc, v1, v2, vcc
	v_cmp_ne_u32_e32 vcc, 0, v4
	s_nop 1
	v_cndmask_b32_e64 v2, 0, 1, vcc
	v_cmp_ne_u32_e32 vcc, 0, v5
	s_nop 1
	v_addc_co_u32_e32 v1, vcc, v1, v2, vcc
	v_cmp_ne_u32_e32 vcc, 0, v6
	s_nop 1
	v_cndmask_b32_e64 v2, 0, 1, vcc
	v_cmp_ne_u32_e32 vcc, 0, v7
	s_nop 1
	v_addc_co_u32_e32 v1, vcc, v1, v2, vcc
	v_cmp_ne_u32_e32 vcc, 0, v8
	s_nop 1
	v_cndmask_b32_e64 v2, 0, 1, vcc
	v_cmp_ne_u32_e32 vcc, 0, v9
	s_nop 1
	v_addc_co_u32_e32 v1, vcc, v1, v2, vcc
	v_cmp_ne_u32_e32 vcc, 0, v10
	s_nop 1
	v_cndmask_b32_e64 v2, 0, 1, vcc
	v_cmp_ne_u32_e32 vcc, 0, v11
	s_nop 1
	v_addc_co_u32_e32 v1, vcc, v1, v2, vcc
	v_cmp_ne_u32_e32 vcc, 0, v12
	s_nop 1
	v_cndmask_b32_e64 v2, 0, 1, vcc
	v_cmp_ne_u32_e32 vcc, 0, v13
	s_nop 1
	v_addc_co_u32_e32 v1, vcc, v1, v2, vcc
	v_cmp_ne_u32_e32 vcc, 0, v14
	s_nop 1
	v_cndmask_b32_e64 v2, 0, 1, vcc
	v_cmp_ne_u32_e32 vcc, 0, v15
	s_nop 1
	v_addc_co_u32_e32 v1, vcc, v1, v2, vcc
	v_max_u32_e32 v1, 1, v1
	v_mov_b32_e32 v2, s82
	ds_write_b32 v2, v3
	ds_write_b32 v2, v1 offset:4
	v_mov_b32_e32 v4, 0x4000
	global_load_dword v5, v4, s[0:1] sc1
	global_load_dword v6, v4, s[0:1] offset:256 sc1
	global_load_dword v7, v4, s[0:1] offset:512 sc1
	global_load_dword v8, v4, s[0:1] offset:768 sc1
	global_load_dword v9, v4, s[0:1] offset:1024 sc1
	global_load_dword v10, v4, s[0:1] offset:1280 sc1
	global_load_dword v11, v4, s[0:1] offset:1536 sc1
	global_load_dword v12, v4, s[0:1] offset:1792 sc1
	v_mov_b32_e32 v14, 0
	v_mov_b32_e32 v15, -1
	s_waitcnt vmcnt(0)
	v_add_u32_e32 v13, -1, v5
	v_and_b32_e32 v13, v13, v5
	v_or_b32_e32 v14, v14, v13
	v_min_u32_e32 v15, v15, v5
	v_add_u32_e32 v13, -1, v6
	v_and_b32_e32 v13, v13, v6
	v_or_b32_e32 v14, v14, v13
	v_min_u32_e32 v15, v15, v6
	v_add_u32_e32 v13, -1, v7
	v_and_b32_e32 v13, v13, v7
	v_or_b32_e32 v14, v14, v13
	v_min_u32_e32 v15, v15, v7
	v_add_u32_e32 v13, -1, v8
	v_and_b32_e32 v13, v13, v8
	v_or_b32_e32 v14, v14, v13
	v_min_u32_e32 v15, v15, v8
	v_add_u32_e32 v13, -1, v9
	v_and_b32_e32 v13, v13, v9
	v_or_b32_e32 v14, v14, v13
	v_min_u32_e32 v15, v15, v9
	v_add_u32_e32 v13, -1, v10
	v_and_b32_e32 v13, v13, v10
	v_or_b32_e32 v14, v14, v13
	v_min_u32_e32 v15, v15, v10
	v_add_u32_e32 v13, -1, v11
	v_and_b32_e32 v13, v13, v11
	v_or_b32_e32 v14, v14, v13
	v_min_u32_e32 v15, v15, v11
	v_add_u32_e32 v13, -1, v12
	v_and_b32_e32 v13, v13, v12
	v_or_b32_e32 v14, v14, v13
	v_min_u32_e32 v15, v15, v12
	v_cmp_eq_u32_e32 vcc, 0, v15
	s_nop 1
	v_cndmask_b32_e64 v14, v14, 1, vcc
	v_cmp_eq_u32_e32 vcc, 0, v14
	s_nop 1
	v_cndmask_b32_e64 v4, 0, 1, vcc
	ds_write_b32 v2, v4 offset:8

.LBB0_184:
	s_andn2_saveexec_b64 s[6:7], s[6:7]
	s_cbranch_execz .LBB0_202
	v_mov_b32_e32 v2, s82
	ds_read_b32 v2, v2 offset:8
	s_waitcnt lgkmcnt(0)
	v_cmp_ne_u32_e32 vcc, 0, v2
	s_cbranch_vccnz .Lxb_local_wi
	s_mov_b64 s[6:7], exec
	buffer_wbl2 sc1
	s_waitcnt lgkmcnt(0)
	s_waitcnt vmcnt(0)
	v_mbcnt_lo_u32_b32 v2, s6, 0
	v_mbcnt_hi_u32_b32 v2, s7, v2
	v_cmp_eq_u32_e32 vcc, 0, v2
	s_and_saveexec_b64 s[8:9], vcc
	s_cbranch_execz .LBB0_187
	s_bcnt1_i32_b64 s6, s[6:7]
	v_mov_b32_e32 v5, s6
	v_readlane_b32 s6, v253, 18
	v_readlane_b32 s7, v253, 19
	s_nop 4
	global_atomic_add v5, v3, v5, s[6:7] sc0

.Lxb_local_wi:
	v_readlane_b32 s6, v253, 16
	v_readlane_b32 s7, v253, 17
	s_waitcnt vmcnt(0)
	buffer_inv sc1
	s_nop 2
	global_atomic_add v3, v247, s[6:7]
	s_waitcnt vmcnt(0)

.LBB0_631:
	s_or_b64 exec, exec, s[8:9]
	s_lshr_b32 s46, s83, 5
	s_lshl_b32 s46, s46, 4
	s_bitcmp1_b32 s83, 4
	s_addc_u32 s46, s46, 0
	s_cmpk_lt_i32 s46, 0x80
	s_cbranch_scc0 .LBB0_658
	v_readlane_b32 s15, v252, 4
	s_lshl_b32 s8, s15, 6
	v_and_b32_e32 v2, 31, v196
	s_and_b32 s12, s8, 64
	s_lshl_b32 s47, s14, 7
	v_or_b32_e32 v2, s12, v2
	v_or_b32_e32 v6, s47, v2
	s_lshl_b32 s13, s15, 4
	v_lshlrev_b32_e32 v6, 2, v6
	s_and_b32 s8, s13, 0xffffffe0
	global_load_dword v53, v6, s[6:7]
	global_load_dword v55, v6, s[6:7] offset:128
	s_lshl_b32 s6, s14, 9
	s_add_u32 s6, s0, s6
	s_addc_u32 s7, s1, 0
	s_ashr_i32 s9, s8, 31
	v_ashrrev_i32_e32 v10, 5, v196
	s_lshl_b64 s[0:1], s[8:9], 2
	s_add_u32 s0, s6, s0
	v_lshlrev_b32_e32 v6, 2, v10
	s_addc_u32 s1, s7, s1
	v_ashrrev_i32_e32 v7, 31, v6
	v_lshl_add_u64 v[8:9], v[6:7], 2, s[0:1]
	global_load_dwordx4 v[36:39], v[8:9], off offset:96
	global_load_dwordx4 v[40:43], v[8:9], off offset:64
	global_load_dwordx4 v[44:47], v[8:9], off offset:32
	global_load_dwordx4 v[48:51], v[8:9], off
	v_mov_b32_e32 v9, s13
	s_movk_i32 s0, 0xffe0
	v_bfi_b32 v9, s0, v9, v196
	s_or_b32 s34, s15, 1
	s_lshl_b32 s0, s14, 8
	s_add_u32 s42, s36, s0
	s_addc_u32 s43, s37, 0
	s_add_u32 s44, s92, s0
	v_bfe_u32 v8, v196, 2, 2
	s_addc_u32 s45, s93, 0
	v_lshlrev_b32_e32 v11, 4, v10
	v_lshl_or_b32 v8, v10, 3, v8
	v_lshlrev_b32_e32 v10, 2, v196
	s_cmp_gt_i32 s15, -1
	v_and_b32_e32 v7, 16, v196
	v_and_b32_e32 v10, 12, v10
	s_cselect_b64 s[0:1], -1, 0
	s_cmp_gt_i32 s34, 1
	s_movk_i32 s22, 0x140
	v_or3_b32 v7, v7, v10, s12
	s_cselect_b64 s[6:7], -1, 0
	s_cmp_gt_i32 s34, 2
	v_mul_lo_u32 v8, v8, s22
	v_lshlrev_b32_e32 v7, 1, v7
	v_add_u32_e32 v6, s8, v6
	s_cselect_b64 s[8:9], -1, 0
	s_cmp_gt_i32 s34, 3
	v_add3_u32 v60, 0, v8, v7
	v_lshl_add_u32 v7, v2, 2, 0
	s_cselect_b64 s[12:13], -1, 0
	s_cmp_gt_i32 s34, 4
	v_lshlrev_b32_e32 v2, 4, v5
	v_mul_lo_u32 v9, v9, s48
	s_cselect_b64 s[14:15], -1, 0
	s_cmp_gt_i32 s34, 5
	v_lshlrev_b32_e32 v8, 2, v244
	v_add_u32_e32 v52, 0, v2
	v_add_u32_e32 v9, 0, v9
	s_cselect_b64 s[22:23], -1, 0
	s_cmp_gt_i32 s34, 6
	v_mul_lo_u32 v6, v6, s65
	s_movk_i32 s40, 0x80
	v_add_u32_e32 v54, v52, v2
	v_lshl_add_u64 v[56:57], s[42:43], 0, v[2:3]
	v_lshl_add_u64 v[58:59], s[44:45], 0, v[2:3]
	v_add_u32_e32 v2, 0, v8
	v_add_u32_e32 v61, 0x8800, v60
	s_cselect_b64 s[34:35], -1, 0
	v_cmp_gt_i32_e64 s[40:41], s40, v244
	v_add_u32_e32 v62, 0x19000, v2
	s_lshl_b32 s94, s47, 1
	v_lshlrev_b32_e32 v2, 1, v4
	v_add_u32_e32 v63, v7, v6
	v_add_u32_e32 v64, v9, v11
	s_branch .LBB0_634
.LBB0_633:
	s_or_b64 exec, exec, s[42:43]
	s_add_i32 s46, s46, 2
	s_and_b32 s48, s46, 14
	s_cmp_eq_u32 s48, 0
	s_movk_i32 s48, 0x110
	s_barrier
	s_cbranch_scc1 .LBB0_658

.LBB0_826:
	s_cmp_gt_i32 s84, s40
	s_cselect_b64 s[0:1], -1, 0
	s_cmp_ge_i32 s40, s85
	s_cselect_b64 s[6:7], -1, 0
	s_or_b64 s[0:1], s[0:1], s[6:7]
	s_mov_b64 s[80:81], 0
	s_and_b64 vcc, exec, s[0:1]
	s_cbranch_vccnz .LBB0_848
	v_writelane_b32 v254, s45, 45
	v_writelane_b32 v254, s42, 46
	s_nop 1
	v_writelane_b32 v254, s43, 47
	s_nop 0
	v_readlane_b32 s0, v254, 44
	s_cmpk_gt_i32 s44, 0x1ff
	s_nop 0
	v_writelane_b32 v254, s0, 44
	v_writelane_b32 v254, s44, 48
	s_cbranch_scc1 .LBB0_836
	v_ashrrev_i32_e32 v2, 1, v243
	s_movk_i32 s6, 0x90
	v_ashrrev_i32_e32 v10, 5, v242
	v_mul_lo_u32 v4, v2, s6
	v_add_u32_e32 v99, 0xffffff80, v2
	v_add_u32_e32 v98, 0, v4
	v_lshlrev_b32_e32 v6, 2, v10
	v_and_b32_e32 v96, 31, v242
	s_waitcnt lgkmcnt(0)
	v_mad_u64_u32 v[4:5], s[0:1], v2, 48, v[98:99]
	v_or_b32_e32 v2, 2, v6
	v_cmp_gt_i32_e64 s[44:45], v2, v96
	v_or_b32_e32 v2, 3, v6
	v_cmp_gt_i32_e64 s[46:47], v2, v96
	v_add_u32_e32 v2, 8, v6
	v_cmp_gt_i32_e64 s[48:49], v2, v96
	v_add_u32_e32 v2, 9, v6
	v_cmp_gt_i32_e64 s[50:51], v2, v96
	v_add_u32_e32 v2, 10, v6
	v_cmp_gt_i32_e64 s[52:53], v2, v96
	v_add_u32_e32 v2, 11, v6
	v_cmp_gt_i32_e64 s[54:55], v2, v96
	v_add_u32_e32 v2, 16, v6
	v_cmp_gt_i32_e64 s[56:57], v2, v96
	v_add_u32_e32 v2, 17, v6
	v_cmp_gt_i32_e64 s[58:59], v2, v96
	v_add_u32_e32 v2, 18, v6
	v_cmp_gt_i32_e64 s[60:61], v2, v96
	v_add_u32_e32 v2, 19, v6
	v_cmp_gt_i32_e64 s[62:63], v2, v96
	v_add_u32_e32 v2, 24, v6
	v_cmp_gt_i32_e64 s[64:65], v2, v96
	v_add_u32_e32 v2, 25, v6
	v_cmp_gt_i32_e64 s[66:67], v2, v96
	v_add_u32_e32 v2, 26, v6
	s_movk_i32 s0, 0x300
	v_and_b32_e32 v11, 1, v243
	v_bfe_u32 v5, v242, 2, 2
	v_lshlrev_b32_e32 v12, 4, v10
	v_lshlrev_b32_e32 v8, 3, v10
	v_cmp_gt_i32_e64 s[68:69], v2, v96
	v_add_u32_e32 v2, 27, v6
	v_mul_lo_u32 v10, v10, s0
	s_movk_i32 s0, 0xc0
	v_lshlrev_b32_e32 v114, 6, v11
	v_cmp_gt_i32_e64 s[70:71], v2, v96
	v_lshlrev_b32_e32 v2, 5, v11
	v_cmp_eq_u32_e64 s[72:73], 0, v11
	v_mad_u32_u24 v5, v5, s0, v10
	v_lshlrev_b32_e32 v10, 1, v242
	v_and_b32_e32 v11, 3, v242
	v_and_b32_e32 v10, 32, v10
	v_lshlrev_b32_e32 v11, 3, v11
	v_ashrrev_i32_e32 v9, 31, v8
	v_or3_b32 v115, v5, v10, v11
	v_mov_b64_e32 v[10:11], 0x2b300040
	v_ashrrev_i32_e32 v7, 31, v6
	v_lshlrev_b32_e32 v5, 4, v96
	v_readlane_b32 s0, v254, 44
	v_lshl_add_u64 v[100:101], v[8:9], 1, v[10:11]
	v_mov_b64_e32 v[8:9], 0x37300040
	v_readlane_b32 s14, v254, 48
	v_mov_b32_e32 v97, v3
	v_cmp_gt_u32_e64 s[38:39], 32, v242
	v_cmp_gt_i32_e64 s[40:41], v6, v96
	v_cmp_lt_i32_e64 s[42:43], v6, v96
	v_mad_u32_u24 v116, v96, s6, v12
	s_lshl_b32 s12, s0, 6
	v_lshl_add_u64 v[102:103], v[6:7], 1, v[8:9]
	v_lshlrev_b32_e32 v104, 1, v2
	v_lshlrev_b32_e32 v117, 2, v5
	v_add_u32_e32 v118, v4, v114
	s_lshr_b32 s13, s14, 5
	s_lshl_b32 s13, s13, 6
	s_and_b32 s14, s14, 31
	s_or_b32 s14, s14, s13
	s_mov_b32 s13, s14

.LBB0_834:
	v_lshl_add_u64 v[12:13], s[90:91], 0, v[106:107]
	s_mov_b64 s[0:1], 0x42500000
	v_lshl_add_u64 v[24:25], v[12:13], 0, s[0:1]
	s_mov_b32 s0, 0x42500000
	v_lshl_add_u64 v[8:9], s[90:91], 0, v[108:109]
	v_lshl_add_u64 v[4:5], s[90:91], 0, v[110:111]
	v_add_co_u32_e32 v12, vcc, s0, v12
	global_load_dwordx4 v[92:95], v[4:5], off offset:-32
	global_load_dwordx4 v[88:91], v[4:5], off
	global_load_dwordx4 v[84:87], v[4:5], off offset:32
	s_nop 0
	global_load_dwordx4 v[4:7], v[8:9], off
	s_nop 0
	global_load_dwordx4 v[8:11], v[8:9], off offset:-16
	v_addc_co_u32_e32 v13, vcc, 0, v13, vcc
	global_load_dwordx4 v[12:15], v[12:13], off
	s_nop 0
	global_load_dwordx4 v[16:19], v[24:25], off offset:48
	global_load_dwordx4 v[20:23], v[24:25], off offset:16
	s_nop 0
	global_load_dwordx4 v[24:27], v[24:25], off offset:32
	s_add_i32 s0, s8, 1
	s_cmp_lt_u32 s8, 3
	s_cselect_b64 s[6:7], -1, 0
	s_and_b64 vcc, s[74:75], s[6:7]
	s_cmp_lt_u32 s8, 2
	s_cselect_b64 s[6:7], -1, 0
	s_or_b32 s1, s8, s15
	v_lshl_add_u64 v[108:109], v[108:109], 0, s[22:23]
	v_lshl_add_u64 v[110:111], v[110:111], 0, s[22:23]
	s_mov_b32 s8, s0
	s_waitcnt vmcnt(5)
	v_lshlrev_b32_e32 v31, 16, v5
	s_waitcnt vmcnt(4)
	v_lshlrev_b32_e32 v29, 16, v9
	v_lshlrev_b32_e32 v28, 16, v8
	v_lshlrev_b32_e32 v32, 16, v4
	v_mov_b32_e32 v33, v29
	s_waitcnt vmcnt(3)
	v_mov_b32_e32 v38, v12
	s_waitcnt vmcnt(0)
	v_mov_b32_e32 v39, v26
	v_mov_b32_e32 v30, v32
	v_mov_b32_e32 v34, v28
	v_mov_b32_e32 v35, v31
	v_mov_b32_e32 v36, v24
	v_mov_b32_e32 v37, v14
	v_pk_mul_f32 v[32:33], v[38:39], v[32:33]
	v_and_b32_e32 v9, 0xffff0000, v9
	v_and_b32_e32 v8, 0xffff0000, v8
	v_pk_fma_f32 v[32:33], v[36:37], v[34:35], v[32:33]
	v_mov_b32_e32 v37, v26
	v_mov_b32_e32 v26, v25
	v_and_b32_e32 v5, 0xffff0000, v5
	v_and_b32_e32 v4, 0xffff0000, v4
	v_mov_b32_e32 v34, v12
	v_mov_b32_e32 v35, v14
	v_mov_b32_e32 v14, v13
	v_pk_mul_f32 v[12:13], v[26:27], v[8:9]
	v_pk_mul_f32 v[30:31], v[36:37], v[30:31]
	v_pk_fma_f32 v[12:13], v[14:15], v[4:5], v[12:13]
	v_pk_mul_f32 v[4:5], v[26:27], v[4:5]
	v_pk_fma_f32 v[28:29], v[34:35], v[28:29], v[30:31] neg_lo:[0,0,1] neg_hi:[0,0,1]
	v_pk_fma_f32 v[4:5], v[14:15], v[8:9], v[4:5] neg_lo:[0,0,1] neg_hi:[0,0,1]
	v_mov_b32_e32 v14, v16
	v_cndmask_b32_e64 v26, v12, v4, s[38:39]
	v_cndmask_b32_e64 v27, v13, v5, s[38:39]
	v_lshlrev_b32_e32 v5, 16, v11
	v_lshlrev_b32_e32 v4, 16, v10
	v_mov_b32_e32 v15, v18
	v_and_b32_e32 v9, 0xffff0000, v11
	v_and_b32_e32 v8, 0xffff0000, v10
	v_lshlrev_b32_e32 v11, 16, v7
	v_lshlrev_b32_e32 v10, 16, v6
	v_mov_b32_e32 v12, v20
	v_mov_b32_e32 v13, v22
	v_pk_mul_f32 v[24:25], v[14:15], v[4:5]
	v_mov_b32_e32 v18, v17
	v_pk_fma_f32 v[24:25], v[12:13], v[10:11], v[24:25]
	v_pk_mul_f32 v[10:11], v[14:15], v[10:11]
	v_and_b32_e32 v7, 0xffff0000, v7
	v_pk_fma_f32 v[4:5], v[12:13], v[4:5], v[10:11] neg_lo:[0,0,1] neg_hi:[0,0,1]
	v_and_b32_e32 v6, 0xffff0000, v6
	v_cndmask_b32_e64 v10, v25, v5, s[38:39]
	v_cndmask_b32_e64 v11, v24, v4, s[38:39]
	v_mov_b32_e32 v22, v21
	v_pk_mul_f32 v[4:5], v[18:19], v[8:9]
	v_cndmask_b32_e64 v2, v33, v29, s[38:39]
	v_pk_fma_f32 v[4:5], v[22:23], v[6:7], v[4:5]
	v_pk_mul_f32 v[6:7], v[18:19], v[6:7]
	v_cndmask_b32_e64 v28, v32, v28, s[38:39]
	v_pk_fma_f32 v[6:7], v[22:23], v[8:9], v[6:7] neg_lo:[0,0,1] neg_hi:[0,0,1]
	v_bfe_u32 v13, v2, 16, 1
	v_cndmask_b32_e64 v4, v4, v6, s[38:39]
	v_cndmask_b32_e64 v5, v5, v7, s[38:39]
	v_bfe_u32 v8, v5, 16, 1
	v_bfe_u32 v9, v4, 16, 1
	v_bfe_u32 v6, v27, 16, 1
	v_add3_u32 v9, v4, v9, s19
	v_add3_u32 v8, v5, v8, s19
	v_bfe_u32 v4, v11, 16, 1
	v_bfe_u32 v5, v10, 16, 1
	v_bfe_u32 v12, v28, 16, 1
	v_add3_u32 v2, v2, v13, s19
	v_bfe_u32 v7, v26, 16, 1
	v_add3_u32 v6, v27, v6, s19
	v_add3_u32 v12, v28, v12, s19
	v_add3_u32 v5, v10, v5, s19
	v_add3_u32 v4, v11, v4, s19
	v_lshrrev_b32_e32 v2, 16, v2
	v_add3_u32 v7, v26, v7, s19
	v_lshrrev_b32_e32 v10, 16, v4
	v_lshrrev_b32_e32 v11, 16, v5
	v_lshrrev_b32_e32 v4, 16, v12
	v_and_or_b32 v5, v6, s29, v2
	v_add_u32_e32 v2, 0, v105
	v_and_or_b32 v4, v7, s29, v4
	v_and_or_b32 v7, v8, s29, v11
	v_and_or_b32 v6, v9, s29, v10
	ds_read_b128 v[8:11], v2
	ds_read_b128 v[12:15], v2 offset:32
	s_waitcnt lgkmcnt(1)
	v_mfma_f32_32x32x16_bf16 v[68:83], v[8:11], v[4:7], 0
	ds_read_b128 v[8:11], v2 offset:64
	ds_read_b128 v[122:125], v2 offset:18464
	v_add_u32_e32 v105, 0x1200, v105
	s_waitcnt lgkmcnt(2)
	v_mfma_f32_32x32x16_bf16 v[68:83], v[12:15], v[92:95], v[68:83]
	s_waitcnt lgkmcnt(1)
	v_mfma_f32_32x32x16_bf16 v[68:83], v[8:11], v[88:91], v[68:83]
	ds_read_b128 v[8:11], v2 offset:96
	s_waitcnt lgkmcnt(0)
	v_mfma_f32_32x32x16_bf16 v[68:83], v[8:11], v[84:87], v[68:83]
	ds_read_b128 v[8:11], v2 offset:4608
	s_waitcnt lgkmcnt(0)
	v_mfma_f32_32x32x16_bf16 v[52:67], v[8:11], v[4:7], 0
	ds_read_b128 v[8:11], v2 offset:4640
	s_waitcnt lgkmcnt(0)
	v_mfma_f32_32x32x16_bf16 v[52:67], v[8:11], v[92:95], v[52:67]
	ds_read_b128 v[8:11], v2 offset:4672
	s_waitcnt lgkmcnt(0)
	v_mfma_f32_32x32x16_bf16 v[52:67], v[8:11], v[88:91], v[52:67]
	ds_read_b128 v[8:11], v2 offset:4704
	s_waitcnt lgkmcnt(0)
	v_mfma_f32_32x32x16_bf16 v[52:67], v[8:11], v[84:87], v[52:67]
	ds_read_b128 v[8:11], v2 offset:9216
	s_waitcnt lgkmcnt(0)
	v_mfma_f32_32x32x16_bf16 v[36:51], v[8:11], v[4:7], 0
	ds_read_b128 v[8:11], v2 offset:9248
	s_nop 7
	v_mul_f32_e32 v52, 0x3e38aa3b, v52
	v_mul_f32_e32 v53, 0x3e38aa3b, v53
	v_cndmask_b32_e32 v52, v52, v249, vcc
	v_cndmask_b32_e32 v53, v53, v249, vcc
	v_mul_f32_e32 v54, 0x3e38aa3b, v54
	v_mul_f32_e32 v55, 0x3e38aa3b, v55
	s_waitcnt lgkmcnt(0)
	v_mfma_f32_32x32x16_bf16 v[36:51], v[8:11], v[92:95], v[36:51]
	ds_read_b128 v[8:11], v2 offset:9280
	v_cndmask_b32_e32 v54, v54, v249, vcc
	v_cndmask_b32_e32 v55, v55, v249, vcc
	v_mul_f32_e32 v56, 0x3e38aa3b, v56
	v_mul_f32_e32 v57, 0x3e38aa3b, v57
	v_cndmask_b32_e32 v56, v56, v249, vcc
	v_cndmask_b32_e32 v57, v57, v249, vcc
	s_waitcnt lgkmcnt(0)
	v_mfma_f32_32x32x16_bf16 v[36:51], v[8:11], v[88:91], v[36:51]
	ds_read_b128 v[8:11], v2 offset:9312
	v_mul_f32_e32 v58, 0x3e38aa3b, v58
	v_mul_f32_e32 v59, 0x3e38aa3b, v59
	v_cndmask_b32_e32 v58, v58, v249, vcc
	v_cndmask_b32_e32 v59, v59, v249, vcc
	v_mul_f32_e32 v60, 0x3e38aa3b, v60
	v_mul_f32_e32 v61, 0x3e38aa3b, v61
	s_waitcnt lgkmcnt(0)
	v_mfma_f32_32x32x16_bf16 v[36:51], v[8:11], v[84:87], v[36:51]
	ds_read_b128 v[8:11], v2 offset:13824
	v_cndmask_b32_e32 v60, v60, v249, vcc
	v_cndmask_b32_e32 v61, v61, v249, vcc
	v_mul_f32_e32 v62, 0x3e38aa3b, v62
	v_mul_f32_e32 v63, 0x3e38aa3b, v63
	v_cndmask_b32_e32 v62, v62, v249, vcc
	v_cndmask_b32_e32 v63, v63, v249, vcc
	s_waitcnt lgkmcnt(0)
	v_mfma_f32_32x32x16_bf16 v[20:35], v[8:11], v[4:7], 0
	ds_read_b128 v[8:11], v2 offset:13856
	v_mul_f32_e32 v64, 0x3e38aa3b, v64
	v_mul_f32_e32 v65, 0x3e38aa3b, v65
	v_mul_f32_e32 v66, 0x3e38aa3b, v66
	v_mul_f32_e32 v67, 0x3e38aa3b, v67
	v_cndmask_b32_e32 v64, v64, v249, vcc
	v_cndmask_b32_e32 v65, v65, v249, vcc
	s_waitcnt lgkmcnt(0)
	v_mfma_f32_32x32x16_bf16 v[20:35], v[8:11], v[92:95], v[20:35]
	ds_read_b128 v[8:11], v2 offset:13888
	v_cndmask_b32_e32 v66, v66, v249, vcc
	v_cndmask_b32_e32 v67, v67, v249, vcc
	s_and_b64 vcc, s[74:75], s[6:7]
	v_mul_f32_e32 v36, 0x3e38aa3b, v36
	s_cmp_eq_u32 s1, 0
	s_waitcnt lgkmcnt(0)
	v_mfma_f32_32x32x16_bf16 v[20:35], v[8:11], v[88:91], v[20:35]
	ds_read_b128 v[8:11], v2 offset:13920
	s_waitcnt lgkmcnt(0)
	v_mfma_f32_32x32x16_bf16 v[20:35], v[8:11], v[84:87], v[20:35]
	ds_read_b128 v[8:11], v2 offset:18432
	s_waitcnt lgkmcnt(0)
	v_mfma_f32_32x32x16_bf16 v[4:19], v[8:11], v[4:7], 0
	s_nop 8
	v_mul_f32_e32 v20, 0x3e38aa3b, v20
	v_mfma_f32_32x32x16_bf16 v[4:19], v[122:125], v[92:95], v[4:19]
	ds_read_b128 v[92:95], v2 offset:18496
	s_waitcnt lgkmcnt(0)
	v_mfma_f32_32x32x16_bf16 v[4:19], v[92:95], v[88:91], v[4:19]
	ds_read_b128 v[88:91], v2 offset:18528
	v_mul_f32_e32 v2, 0x3e38aa3b, v68
	v_cndmask_b32_e64 v2, v249, v2, s[40:41]
	v_mul_f32_e32 v68, 0x3e38aa3b, v69
	v_mul_f32_e32 v69, 0x3e38aa3b, v70
	v_mul_f32_e32 v70, 0x3e38aa3b, v71
	v_cndmask_b32_e64 v2, v2, v249, s[74:75]
	v_cndmask_b32_e64 v68, v68, v249, s[76:77]
	v_cndmask_b32_e64 v69, v249, v69, s[44:45]
	v_cndmask_b32_e64 v70, v249, v70, s[46:47]
	v_mul_f32_e32 v71, 0x3e38aa3b, v72
	v_mul_f32_e32 v72, 0x3e38aa3b, v73
	s_waitcnt lgkmcnt(0)
	v_mfma_f32_32x32x16_bf16 v[4:19], v[88:91], v[84:87], v[4:19]
	v_max3_f32 v84, v2, s21, v68
	v_cndmask_b32_e64 v69, v69, v249, s[74:75]
	v_cndmask_b32_e64 v70, v70, v249, s[74:75]
	v_cndmask_b32_e64 v71, v249, v71, s[48:49]
	v_cndmask_b32_e64 v72, v249, v72, s[50:51]
	v_mul_f32_e32 v73, 0x3e38aa3b, v74
	v_mul_f32_e32 v74, 0x3e38aa3b, v75
	v_max3_f32 v84, v84, v69, v70
	v_cndmask_b32_e64 v71, v71, v249, s[74:75]
	v_cndmask_b32_e64 v72, v72, v249, s[74:75]
	v_cndmask_b32_e64 v73, v249, v73, s[52:53]
	v_cndmask_b32_e64 v74, v249, v74, s[54:55]
	v_mul_f32_e32 v75, 0x3e38aa3b, v76
	v_mul_f32_e32 v76, 0x3e38aa3b, v77
	v_max3_f32 v84, v84, v71, v72
	v_cndmask_b32_e64 v73, v73, v249, s[74:75]
	v_cndmask_b32_e64 v74, v74, v249, s[74:75]
	v_cndmask_b32_e64 v75, v249, v75, s[56:57]
	v_cndmask_b32_e64 v76, v249, v76, s[58:59]
	v_mul_f32_e32 v77, 0x3e38aa3b, v78
	v_mul_f32_e32 v78, 0x3e38aa3b, v79
	v_max3_f32 v84, v84, v73, v74
	v_cndmask_b32_e64 v75, v75, v249, s[74:75]
	v_cndmask_b32_e64 v76, v76, v249, s[74:75]
	v_cndmask_b32_e64 v77, v249, v77, s[60:61]
	v_cndmask_b32_e64 v78, v249, v78, s[62:63]
	v_mul_f32_e32 v79, 0x3e38aa3b, v80
	v_mul_f32_e32 v80, 0x3e38aa3b, v81
	v_max3_f32 v84, v84, v75, v76
	v_cndmask_b32_e64 v77, v77, v249, s[74:75]
	v_cndmask_b32_e64 v78, v78, v249, s[74:75]
	v_cndmask_b32_e64 v79, v249, v79, s[64:65]
	v_cndmask_b32_e64 v80, v249, v80, s[66:67]
	v_mul_f32_e32 v81, 0x3e38aa3b, v82
	v_mul_f32_e32 v82, 0x3e38aa3b, v83
	v_max3_f32 v84, v84, v77, v78
	v_cndmask_b32_e64 v79, v79, v249, s[74:75]
	v_cndmask_b32_e64 v80, v80, v249, s[74:75]
	v_cndmask_b32_e64 v81, v249, v81, s[68:69]
	v_cndmask_b32_e64 v82, v249, v82, s[70:71]
	v_max3_f32 v84, v84, v79, v80
	v_cndmask_b32_e64 v81, v81, v249, s[74:75]
	v_cndmask_b32_e64 v82, v82, v249, s[74:75]
	v_max3_f32 v83, v84, v81, v82
	v_max3_f32 v83, v83, v52, v53
	v_max3_f32 v83, v83, v54, v55
	v_max3_f32 v83, v83, v56, v57
	v_max3_f32 v83, v83, v58, v59
	v_max3_f32 v83, v83, v60, v61
	v_max3_f32 v83, v83, v62, v63
	v_max3_f32 v83, v83, v64, v65
	v_cndmask_b32_e32 v84, v36, v249, vcc
	v_mul_f32_e32 v36, 0x3e38aa3b, v37
	v_max3_f32 v83, v83, v66, v67
	v_cndmask_b32_e32 v85, v36, v249, vcc
	v_mul_f32_e32 v37, 0x3e38aa3b, v38
	v_max3_f32 v36, v83, v84, v85
	v_cndmask_b32_e32 v83, v37, v249, vcc
	v_mul_f32_e32 v37, 0x3e38aa3b, v39
	v_cndmask_b32_e32 v86, v37, v249, vcc
	v_mul_f32_e32 v37, 0x3e38aa3b, v40
	v_cndmask_b32_e32 v87, v37, v249, vcc
	v_mul_f32_e32 v37, 0x3e38aa3b, v41
	v_cndmask_b32_e32 v88, v37, v249, vcc
	v_mul_f32_e32 v37, 0x3e38aa3b, v42
	v_cndmask_b32_e32 v89, v37, v249, vcc
	v_mul_f32_e32 v37, 0x3e38aa3b, v43
	v_cndmask_b32_e32 v90, v37, v249, vcc
	v_mul_f32_e32 v37, 0x3e38aa3b, v44
	v_cndmask_b32_e32 v91, v37, v249, vcc
	v_mul_f32_e32 v37, 0x3e38aa3b, v45
	v_cndmask_b32_e32 v92, v37, v249, vcc
	v_mul_f32_e32 v37, 0x3e38aa3b, v46
	v_cndmask_b32_e32 v93, v37, v249, vcc
	v_mul_f32_e32 v37, 0x3e38aa3b, v47
	v_cndmask_b32_e32 v94, v37, v249, vcc
	v_mul_f32_e32 v37, 0x3e38aa3b, v48
	v_cndmask_b32_e32 v95, v37, v249, vcc
	v_mul_f32_e32 v37, 0x3e38aa3b, v49
	v_cndmask_b32_e32 v121, v37, v249, vcc
	v_mul_f32_e32 v37, 0x3e38aa3b, v50
	v_cndmask_b32_e32 v122, v37, v249, vcc
	v_mul_f32_e32 v37, 0x3e38aa3b, v51
	v_cndmask_b32_e32 v123, v37, v249, vcc
	s_cselect_b64 vcc, -1, 0
	v_cndmask_b32_e32 v124, v20, v249, vcc
	v_mul_f32_e32 v20, 0x3e38aa3b, v21
	v_mul_f32_e32 v21, 0x3e38aa3b, v22
	v_max3_f32 v36, v36, v83, v86
	v_cndmask_b32_e32 v126, v21, v249, vcc
	v_mul_f32_e32 v21, 0x3e38aa3b, v23
	v_max3_f32 v36, v36, v87, v88
	v_cndmask_b32_e32 v127, v21, v249, vcc
	v_mul_f32_e32 v21, 0x3e38aa3b, v24
	v_max3_f32 v36, v36, v89, v90
	v_cndmask_b32_e32 v128, v21, v249, vcc
	v_mul_f32_e32 v21, 0x3e38aa3b, v25
	v_max3_f32 v36, v36, v91, v92
	v_cndmask_b32_e32 v129, v21, v249, vcc
	v_mul_f32_e32 v21, 0x3e38aa3b, v26
	v_max3_f32 v36, v36, v93, v94
	v_cndmask_b32_e32 v130, v21, v249, vcc
	v_mul_f32_e32 v21, 0x3e38aa3b, v27
	v_max3_f32 v36, v36, v95, v121
	v_cndmask_b32_e32 v131, v21, v249, vcc
	v_mul_f32_e32 v21, 0x3e38aa3b, v28
	v_max3_f32 v36, v36, v122, v123
	v_cndmask_b32_e32 v125, v20, v249, vcc
	v_cndmask_b32_e32 v132, v21, v249, vcc
	v_mul_f32_e32 v21, 0x3e38aa3b, v29
	v_mul_f32_e32 v4, 0x3e38aa3b, v4
	v_max3_f32 v20, v36, v124, v125
	v_cndmask_b32_e32 v133, v21, v249, vcc
	v_mul_f32_e32 v21, 0x3e38aa3b, v30
	v_cndmask_b32_e64 v140, v4, v249, s[40:41]
	v_mul_f32_e32 v4, 0x3e38aa3b, v5
	v_mul_f32_e32 v5, 0x3e38aa3b, v6
	v_max3_f32 v20, v20, v126, v127
	v_cndmask_b32_e32 v134, v21, v249, vcc
	v_mul_f32_e32 v21, 0x3e38aa3b, v31
	v_cndmask_b32_e64 v142, v5, v249, s[44:45]
	v_mul_f32_e32 v5, 0x3e38aa3b, v7
	v_max3_f32 v20, v20, v128, v129
	v_cndmask_b32_e32 v135, v21, v249, vcc
	v_mul_f32_e32 v21, 0x3e38aa3b, v32
	v_cndmask_b32_e64 v143, v5, v249, s[46:47]
	v_mul_f32_e32 v5, 0x3e38aa3b, v8
	v_max3_f32 v20, v20, v130, v131
	v_cndmask_b32_e32 v136, v21, v249, vcc
	v_mul_f32_e32 v21, 0x3e38aa3b, v33
	v_cndmask_b32_e64 v144, v5, v249, s[48:49]
	v_mul_f32_e32 v5, 0x3e38aa3b, v9
	v_max3_f32 v20, v20, v132, v133
	v_cndmask_b32_e32 v137, v21, v249, vcc
	v_mul_f32_e32 v21, 0x3e38aa3b, v34
	v_cndmask_b32_e64 v145, v5, v249, s[50:51]
	v_mul_f32_e32 v5, 0x3e38aa3b, v10
	v_max3_f32 v20, v20, v134, v135
	v_cndmask_b32_e32 v138, v21, v249, vcc
	v_mul_f32_e32 v21, 0x3e38aa3b, v35
	v_cndmask_b32_e64 v146, v5, v249, s[52:53]
	v_mul_f32_e32 v5, 0x3e38aa3b, v11
	v_max3_f32 v20, v20, v136, v137
	v_cndmask_b32_e32 v139, v21, v249, vcc
	v_cndmask_b32_e64 v147, v5, v249, s[54:55]
	v_mul_f32_e32 v5, 0x3e38aa3b, v12
	v_max3_f32 v20, v20, v138, v139
	v_cndmask_b32_e64 v141, v249, v4, s[42:43]
	v_cndmask_b32_e64 v12, v5, v249, s[56:57]
	v_mul_f32_e32 v5, 0x3e38aa3b, v13
	v_max3_f32 v4, v20, v140, v141
	v_cndmask_b32_e64 v13, v5, v249, s[58:59]
	v_mul_f32_e32 v5, 0x3e38aa3b, v14
	v_max3_f32 v4, v4, v142, v143
	v_cndmask_b32_e64 v14, v5, v249, s[60:61]
	v_mul_f32_e32 v5, 0x3e38aa3b, v15
	v_max3_f32 v4, v4, v144, v145
	v_cndmask_b32_e64 v15, v5, v249, s[62:63]
	v_mul_f32_e32 v5, 0x3e38aa3b, v16
	v_max3_f32 v4, v4, v146, v147
	v_cndmask_b32_e64 v16, v5, v249, s[64:65]
	v_mul_f32_e32 v5, 0x3e38aa3b, v17
	v_max3_f32 v4, v4, v12, v13
	v_cndmask_b32_e64 v17, v5, v249, s[66:67]
	v_mul_f32_e32 v5, 0x3e38aa3b, v18
	v_max3_f32 v4, v4, v14, v15
	v_cndmask_b32_e64 v18, v5, v249, s[68:69]
	v_mul_f32_e32 v5, 0x3e38aa3b, v19
	v_max3_f32 v4, v4, v16, v17
	v_cndmask_b32_e64 v19, v5, v249, s[70:71]
	v_max3_f32 v4, v4, v18, v19
	v_mov_b32_e32 v5, v4
	s_nop 1
	v_permlane32_swap_b32 v5, v4
	s_nop 1
	s_cmp_lg_u32 s0, 4
	v_max3_f32 v4, v5, v4, v119
	v_sub_f32_e32 v2, v2, v4
	v_exp_f32_e32 v2, v2
	v_sub_f32_e32 v5, v68, v4
	v_exp_f32_e32 v5, v5
	v_sub_f32_e32 v28, v82, v4
	v_add_f32_e32 v6, 0, v2
	v_exp_f32_e32 v28, v28
	v_add_f32_e32 v7, v5, v6
	v_sub_f32_e32 v6, v69, v4
	v_exp_f32_e32 v6, v6
	v_sub_f32_e32 v36, v59, v4
	v_exp_f32_e32 v36, v36
	v_sub_f32_e32 v44, v67, v4
	v_add_f32_e32 v8, v6, v7
	v_sub_f32_e32 v7, v70, v4
	v_exp_f32_e32 v7, v7
	v_exp_f32_e32 v44, v44
	v_sub_f32_e32 v68, v131, v4
	v_exp_f32_e32 v68, v68
	v_add_f32_e32 v9, v7, v8
	v_sub_f32_e32 v8, v71, v4
	v_exp_f32_e32 v8, v8
	v_sub_f32_e32 v12, v12, v4
	v_sub_f32_e32 v13, v13, v4
	v_add_f32_e32 v10, v8, v9
	v_sub_f32_e32 v9, v72, v4
	v_exp_f32_e32 v9, v9
	s_nop 0
	v_add_f32_e32 v11, v9, v10
	v_sub_f32_e32 v10, v73, v4
	v_exp_f32_e32 v10, v10
	s_nop 0
	v_add_f32_e32 v20, v10, v11
	v_sub_f32_e32 v11, v74, v4
	v_exp_f32_e32 v11, v11
	s_nop 0
	v_add_f32_e32 v21, v11, v20
	v_sub_f32_e32 v20, v75, v4
	v_exp_f32_e32 v20, v20
	s_nop 0
	v_add_f32_e32 v22, v20, v21
	v_sub_f32_e32 v21, v76, v4
	v_exp_f32_e32 v21, v21
	v_sub_f32_e32 v76, v139, v4
	v_exp_f32_e32 v76, v76
	v_add_f32_e32 v23, v21, v22
	v_sub_f32_e32 v22, v77, v4
	v_exp_f32_e32 v22, v22
	s_nop 0
	v_add_f32_e32 v24, v22, v23
	v_sub_f32_e32 v23, v78, v4
	v_exp_f32_e32 v23, v23
	s_nop 0
	v_add_f32_e32 v25, v23, v24
	v_sub_f32_e32 v24, v79, v4
	v_exp_f32_e32 v24, v24
	s_nop 0
	v_add_f32_e32 v26, v24, v25
	v_sub_f32_e32 v25, v80, v4
	v_exp_f32_e32 v25, v25
	s_nop 0
	v_add_f32_e32 v27, v25, v26
	v_sub_f32_e32 v26, v81, v4
	v_exp_f32_e32 v26, v26
	s_nop 0
	v_add_f32_e32 v27, v26, v27
	v_add_f32_e32 v29, v28, v27
	v_sub_f32_e32 v27, v52, v4
	v_exp_f32_e32 v27, v27
	v_sub_f32_e32 v52, v90, v4
	v_exp_f32_e32 v52, v52
	v_add_f32_e32 v30, v27, v29
	v_sub_f32_e32 v29, v53, v4
	v_exp_f32_e32 v29, v29
	s_nop 0
	v_add_f32_e32 v31, v29, v30
	v_sub_f32_e32 v30, v54, v4
	v_exp_f32_e32 v30, v30
	s_nop 0
	v_add_f32_e32 v32, v30, v31
	v_sub_f32_e32 v31, v55, v4
	v_exp_f32_e32 v31, v31
	s_nop 0
	v_add_f32_e32 v33, v31, v32
	v_sub_f32_e32 v32, v56, v4
	v_exp_f32_e32 v32, v32
	s_nop 0
	v_add_f32_e32 v34, v32, v33
	v_sub_f32_e32 v33, v57, v4
	v_exp_f32_e32 v33, v33
	s_nop 0
	v_add_f32_e32 v35, v33, v34
	v_sub_f32_e32 v34, v58, v4
	v_exp_f32_e32 v34, v34
	s_nop 0
	v_add_f32_e32 v35, v34, v35
	v_add_f32_e32 v37, v36, v35
	v_sub_f32_e32 v35, v60, v4
	v_exp_f32_e32 v35, v35
	v_sub_f32_e32 v60, v123, v4
	v_exp_f32_e32 v60, v60
	v_add_f32_e32 v38, v35, v37
	v_sub_f32_e32 v37, v61, v4
	v_exp_f32_e32 v37, v37
	s_nop 0
	v_add_f32_e32 v39, v37, v38
	v_sub_f32_e32 v38, v62, v4
	v_exp_f32_e32 v38, v38
	s_nop 0
	v_add_f32_e32 v40, v38, v39
	v_sub_f32_e32 v39, v63, v4
	v_exp_f32_e32 v39, v39
	s_nop 0
	v_add_f32_e32 v41, v39, v40
	v_sub_f32_e32 v40, v64, v4
	v_exp_f32_e32 v40, v40
	s_nop 0
	v_add_f32_e32 v42, v40, v41
	v_sub_f32_e32 v41, v65, v4
	v_exp_f32_e32 v41, v41
	s_nop 0
	v_add_f32_e32 v43, v41, v42
	v_sub_f32_e32 v42, v66, v4
	v_exp_f32_e32 v42, v42
	s_nop 0
	v_add_f32_e32 v43, v42, v43
	v_add_f32_e32 v45, v44, v43
	v_sub_f32_e32 v43, v84, v4
	v_exp_f32_e32 v43, v43
	v_sub_f32_e32 v84, v147, v4
	v_exp_f32_e32 v84, v84
	v_add_f32_e32 v46, v43, v45
	v_sub_f32_e32 v45, v85, v4
	v_exp_f32_e32 v45, v45
	s_nop 0
	v_add_f32_e32 v47, v45, v46
	v_sub_f32_e32 v46, v83, v4
	v_exp_f32_e32 v46, v46
	s_nop 0
	v_add_f32_e32 v48, v46, v47
	v_sub_f32_e32 v47, v86, v4
	v_exp_f32_e32 v47, v47
	s_nop 0
	v_add_f32_e32 v49, v47, v48
	v_sub_f32_e32 v48, v87, v4
	v_exp_f32_e32 v48, v48
	s_nop 0
	v_add_f32_e32 v50, v48, v49
	v_sub_f32_e32 v49, v88, v4
	v_exp_f32_e32 v49, v49
	s_nop 0
	v_add_f32_e32 v51, v49, v50
	v_sub_f32_e32 v50, v89, v4
	v_exp_f32_e32 v50, v50
	s_nop 0
	v_add_f32_e32 v51, v50, v51
	v_add_f32_e32 v53, v52, v51
	v_sub_f32_e32 v51, v91, v4
	v_exp_f32_e32 v51, v51
	s_nop 0
	v_add_f32_e32 v54, v51, v53
	v_sub_f32_e32 v53, v92, v4
	v_exp_f32_e32 v53, v53
	v_cvt_pk_bf16_f32 v92, v2, v5
	v_add_f32_e32 v55, v53, v54
	v_sub_f32_e32 v54, v93, v4
	v_exp_f32_e32 v54, v54
	v_cvt_pk_bf16_f32 v93, v6, v7
	v_add_f32_e32 v56, v54, v55
	v_sub_f32_e32 v55, v94, v4
	v_exp_f32_e32 v55, v55
	v_cvt_pk_bf16_f32 v94, v8, v9
	v_add_f32_e32 v57, v55, v56
	v_sub_f32_e32 v56, v95, v4
	v_exp_f32_e32 v56, v56
	v_cvt_pk_bf16_f32 v95, v10, v11
	v_add_f32_e32 v58, v56, v57
	v_sub_f32_e32 v57, v121, v4
	v_exp_f32_e32 v57, v57
	v_add_u32_e32 v121, 0, v120
	v_add_u32_e32 v2, 0x10200, v121
	v_add_u32_e32 v120, 0x1800, v120
	v_add_f32_e32 v59, v57, v58
	v_sub_f32_e32 v58, v122, v4
	v_exp_f32_e32 v58, v58
	s_nop 0
	v_add_f32_e32 v59, v58, v59
	v_add_f32_e32 v61, v60, v59
	v_sub_f32_e32 v59, v124, v4
	v_exp_f32_e32 v59, v59
	s_nop 0
	v_add_f32_e32 v62, v59, v61
	v_sub_f32_e32 v61, v125, v4
	v_exp_f32_e32 v61, v61
	s_nop 0
	v_add_f32_e32 v63, v61, v62
	v_sub_f32_e32 v62, v126, v4
	v_exp_f32_e32 v62, v62
	v_cvt_pk_bf16_f32 v126, v20, v21
	v_add_f32_e32 v64, v62, v63
	v_sub_f32_e32 v63, v127, v4
	v_exp_f32_e32 v63, v63
	v_cvt_pk_bf16_f32 v127, v22, v23
	v_add_f32_e32 v65, v63, v64
	v_sub_f32_e32 v64, v128, v4
	v_exp_f32_e32 v64, v64
	v_cvt_pk_bf16_f32 v128, v24, v25
	v_add_f32_e32 v66, v64, v65
	v_sub_f32_e32 v65, v129, v4
	v_exp_f32_e32 v65, v65
	v_cvt_pk_bf16_f32 v129, v26, v28
	v_add_f32_e32 v67, v65, v66
	v_sub_f32_e32 v66, v130, v4
	v_exp_f32_e32 v66, v66
	s_nop 0
	v_add_f32_e32 v67, v66, v67
	v_add_f32_e32 v69, v68, v67
	v_sub_f32_e32 v67, v132, v4
	v_exp_f32_e32 v67, v67
	s_nop 0
	v_add_f32_e32 v70, v67, v69
	v_sub_f32_e32 v69, v133, v4
	v_exp_f32_e32 v69, v69
	s_nop 0
	v_add_f32_e32 v71, v69, v70
	v_sub_f32_e32 v70, v134, v4
	v_exp_f32_e32 v70, v70
	s_nop 0
	v_add_f32_e32 v72, v70, v71
	v_sub_f32_e32 v71, v135, v4
	v_exp_f32_e32 v71, v71
	s_nop 0
	v_add_f32_e32 v73, v71, v72
	v_sub_f32_e32 v72, v136, v4
	v_exp_f32_e32 v72, v72
	s_nop 0
	v_add_f32_e32 v74, v72, v73
	v_sub_f32_e32 v73, v137, v4
	v_exp_f32_e32 v73, v73
	s_nop 0
	v_add_f32_e32 v75, v73, v74
	v_sub_f32_e32 v74, v138, v4
	v_exp_f32_e32 v74, v74
	s_nop 0
	v_add_f32_e32 v75, v74, v75
	v_add_f32_e32 v77, v76, v75
	v_sub_f32_e32 v75, v140, v4
	v_exp_f32_e32 v75, v75
	s_nop 0
	v_add_f32_e32 v78, v75, v77
	v_sub_f32_e32 v77, v141, v4
	v_exp_f32_e32 v77, v77
	s_nop 0
	v_add_f32_e32 v79, v77, v78
	v_sub_f32_e32 v78, v142, v4
	v_exp_f32_e32 v78, v78
	s_nop 0
	v_add_f32_e32 v80, v78, v79
	v_sub_f32_e32 v79, v143, v4
	v_exp_f32_e32 v79, v79
	s_nop 0
	v_add_f32_e32 v81, v79, v80
	v_sub_f32_e32 v80, v144, v4
	v_exp_f32_e32 v80, v80
	s_nop 0
	v_add_f32_e32 v82, v80, v81
	v_sub_f32_e32 v81, v145, v4
	v_exp_f32_e32 v81, v81
	s_nop 0
	v_add_f32_e32 v83, v81, v82
	v_sub_f32_e32 v82, v146, v4
	v_exp_f32_e32 v82, v82
	s_nop 0
	v_add_f32_e32 v83, v82, v83
	v_add_f32_e32 v85, v84, v83
	v_exp_f32_e32 v83, v12
	s_nop 0
	v_add_f32_e32 v12, v83, v85
	v_exp_f32_e32 v85, v13
	v_sub_f32_e32 v13, v14, v4
	v_exp_f32_e32 v86, v13
	v_sub_f32_e32 v13, v15, v4
	v_exp_f32_e32 v87, v13
	v_sub_f32_e32 v13, v16, v4
	v_exp_f32_e32 v88, v13
	v_sub_f32_e32 v13, v17, v4
	v_add_f32_e32 v12, v85, v12
	v_exp_f32_e32 v89, v13
	v_sub_f32_e32 v13, v18, v4
	v_add_f32_e32 v12, v86, v12
	v_exp_f32_e32 v90, v13
	v_sub_f32_e32 v13, v19, v4
	v_add_f32_e32 v12, v87, v12
	v_exp_f32_e32 v91, v13
	v_add_f32_e32 v12, v88, v12
	v_add_f32_e32 v12, v89, v12
	v_add_f32_e32 v12, v90, v12
	v_sub_f32_e32 v4, v119, v4
	v_add_f32_e32 v12, v91, v12
	v_exp_f32_e32 v4, v4
	v_mov_b32_e32 v13, v12
	s_nop 1
	v_permlane32_swap_b32 v12, v13
	s_nop 1
	s_nop 0
	v_add_f32_e32 v12, v12, v13
	v_add_f32_e32 v130, v12, v4
	ds_read_b64_tr_b16 v[12:13], v121 offset:36864
	ds_read_b64_tr_b16 v[14:15], v121 offset:38400
	s_waitcnt lgkmcnt(0)
	v_mfma_f32_32x32x16_bf16 v[4:19], v[12:15], v[92:95], 0
	ds_read_b64_tr_b16 v[122:123], v121 offset:39936
	ds_read_b64_tr_b16 v[124:125], v121 offset:41472
	ds_read_b64_tr_b16 v[20:21], v121 offset:43008
	ds_read_b64_tr_b16 v[22:23], v121 offset:44544
	s_waitcnt lgkmcnt(2)
	v_mfma_f32_32x32x16_bf16 v[4:19], v[122:125], v[126:129], v[4:19]
	v_cvt_pk_bf16_f32 v122, v27, v29
	v_cvt_pk_bf16_f32 v123, v30, v31
	v_cvt_pk_bf16_f32 v124, v32, v33
	v_cvt_pk_bf16_f32 v125, v34, v36
	v_cvt_pk_bf16_f32 v36, v35, v37
	v_cvt_pk_bf16_f32 v37, v38, v39
	v_cvt_pk_bf16_f32 v38, v40, v41
	s_waitcnt lgkmcnt(0)
	v_mfma_f32_32x32x16_bf16 v[4:19], v[20:23], v[122:125], v[4:19]
	ds_read_b64_tr_b16 v[20:21], v121 offset:46080
	ds_read_b64_tr_b16 v[22:23], v121 offset:47616
	v_cvt_pk_bf16_f32 v39, v42, v44
	v_cvt_pk_bf16_f32 v40, v43, v45
	v_cvt_pk_bf16_f32 v41, v46, v47
	v_cvt_pk_bf16_f32 v42, v48, v49
	v_cvt_pk_bf16_f32 v43, v50, v52
	v_cvt_pk_bf16_f32 v44, v51, v53
	s_waitcnt lgkmcnt(0)
	v_mfma_f32_32x32x16_bf16 v[4:19], v[20:23], v[36:39], v[4:19]
	ds_read_b64_tr_b16 v[20:21], v121 offset:49152
	ds_read_b64_tr_b16 v[22:23], v121 offset:50688
	v_cvt_pk_bf16_f32 v45, v54, v55
	v_cvt_pk_bf16_f32 v46, v56, v57
	v_cvt_pk_bf16_f32 v47, v58, v60
	v_cvt_pk_bf16_f32 v48, v59, v61
	v_cvt_pk_bf16_f32 v49, v62, v63
	v_cvt_pk_bf16_f32 v50, v64, v65
	s_waitcnt lgkmcnt(0)
	v_mfma_f32_32x32x16_bf16 v[4:19], v[20:23], v[40:43], v[4:19]
	ds_read_b64_tr_b16 v[20:21], v121 offset:52224
	ds_read_b64_tr_b16 v[22:23], v121 offset:53760
	v_cvt_pk_bf16_f32 v51, v66, v68
	v_cvt_pk_bf16_f32 v52, v67, v69
	v_cvt_pk_bf16_f32 v53, v70, v71
	v_cvt_pk_bf16_f32 v54, v72, v73
	v_cvt_pk_bf16_f32 v55, v74, v76
	v_cvt_pk_bf16_f32 v56, v75, v77
	s_waitcnt lgkmcnt(0)
	v_mfma_f32_32x32x16_bf16 v[4:19], v[20:23], v[44:47], v[4:19]
	ds_read_b64_tr_b16 v[20:21], v121 offset:55296
	ds_read_b64_tr_b16 v[22:23], v121 offset:56832
	v_cvt_pk_bf16_f32 v57, v78, v79
	v_cvt_pk_bf16_f32 v58, v80, v81
	v_cvt_pk_bf16_f32 v59, v82, v84
	v_cvt_pk_bf16_f32 v60, v83, v85
	v_cvt_pk_bf16_f32 v61, v86, v87
	v_cvt_pk_bf16_f32 v62, v88, v89
	s_waitcnt lgkmcnt(0)
	v_mfma_f32_32x32x16_bf16 v[4:19], v[20:23], v[48:51], v[4:19]
	ds_read_b64_tr_b16 v[20:21], v121 offset:58368
	ds_read_b64_tr_b16 v[22:23], v121 offset:59904
	v_cvt_pk_bf16_f32 v63, v90, v91
	s_waitcnt lgkmcnt(0)
	v_mfma_f32_32x32x16_bf16 v[4:19], v[20:23], v[52:55], v[4:19]
	ds_read_b64_tr_b16 v[20:21], v121 offset:61440
	ds_read_b64_tr_b16 v[22:23], v121 offset:62976
	s_waitcnt lgkmcnt(0)
	v_mfma_f32_32x32x16_bf16 v[4:19], v[20:23], v[56:59], v[4:19]
	ds_read_b64_tr_b16 v[20:21], v121 offset:64512
	ds_read_b64_tr_b16 v[22:23], v2
	v_add_u32_e32 v2, 0x10240, v121
	s_waitcnt lgkmcnt(0)
	v_mfma_f32_32x32x16_bf16 v[4:19], v[20:23], v[60:63], v[4:19]
	ds_read_b64_tr_b16 v[20:21], v121 offset:36928
	ds_read_b64_tr_b16 v[22:23], v121 offset:38464
	ds_read_b64_tr_b16 v[64:65], v121 offset:40000
	ds_read_b64_tr_b16 v[66:67], v121 offset:41536
	s_waitcnt lgkmcnt(2)
	v_mfma_f32_32x32x16_bf16 v[20:35], v[20:23], v[92:95], 0
	s_waitcnt lgkmcnt(0)
	v_mfma_f32_32x32x16_bf16 v[20:35], v[64:67], v[126:129], v[20:35]
	ds_read_b64_tr_b16 v[64:65], v121 offset:43072
	ds_read_b64_tr_b16 v[66:67], v121 offset:44608
	s_waitcnt lgkmcnt(0)
	v_mfma_f32_32x32x16_bf16 v[20:35], v[64:67], v[122:125], v[20:35]
	ds_read_b64_tr_b16 v[64:65], v121 offset:46144
	ds_read_b64_tr_b16 v[66:67], v121 offset:47680
	s_waitcnt lgkmcnt(0)
	v_mfma_f32_32x32x16_bf16 v[20:35], v[64:67], v[36:39], v[20:35]
	ds_read_b64_tr_b16 v[36:37], v121 offset:49216
	ds_read_b64_tr_b16 v[38:39], v121 offset:50752
	s_waitcnt lgkmcnt(0)
	v_mfma_f32_32x32x16_bf16 v[20:35], v[36:39], v[40:43], v[20:35]
	ds_read_b64_tr_b16 v[36:37], v121 offset:52288
	ds_read_b64_tr_b16 v[38:39], v121 offset:53824
	s_waitcnt lgkmcnt(0)
	v_mfma_f32_32x32x16_bf16 v[20:35], v[36:39], v[44:47], v[20:35]
	ds_read_b64_tr_b16 v[36:37], v121 offset:55360
	ds_read_b64_tr_b16 v[38:39], v121 offset:56896
	s_waitcnt lgkmcnt(0)
	v_mfma_f32_32x32x16_bf16 v[20:35], v[36:39], v[48:51], v[20:35]
	ds_read_b64_tr_b16 v[36:37], v121 offset:58432
	ds_read_b64_tr_b16 v[38:39], v121 offset:59968
	s_waitcnt lgkmcnt(0)
	v_mfma_f32_32x32x16_bf16 v[20:35], v[36:39], v[52:55], v[20:35]
	ds_read_b64_tr_b16 v[36:37], v121 offset:61504
	ds_read_b64_tr_b16 v[38:39], v121 offset:63040
	s_waitcnt lgkmcnt(0)
	v_mfma_f32_32x32x16_bf16 v[20:35], v[36:39], v[56:59], v[20:35]
	ds_read_b64_tr_b16 v[36:37], v121 offset:64576
	ds_read_b64_tr_b16 v[38:39], v2
	v_div_scale_f32 v2, s[6:7], v130, v130, 1.0
	s_mov_b64 s[6:7], 0x800
	s_nop 0
	v_lshl_add_u64 v[106:107], v[106:107], 0, s[6:7]
	s_mov_b64 s[6:7], 0x20000
	s_waitcnt lgkmcnt(0)
	v_mfma_f32_32x32x16_bf16 v[20:35], v[36:39], v[60:63], v[20:35]
	v_rcp_f32_e32 v36, v2
	s_nop 0
	v_fma_f32 v37, -v2, v36, 1.0
	v_fmac_f32_e32 v36, v37, v36
	v_div_scale_f32 v37, vcc, 1.0, v130, 1.0
	v_mul_f32_e32 v38, v37, v36
	v_fma_f32 v39, -v2, v38, v37
	v_fmac_f32_e32 v38, v39, v36
	v_fma_f32 v2, -v2, v38, v37
	v_div_fmas_f32 v2, v2, v36, v38
	v_div_fixup_f32 v2, v2, v130, 1.0
	v_pk_mul_f32 v[4:5], v[2:3], v[4:5] op_sel_hi:[0,1]
	v_pk_mul_f32 v[6:7], v[2:3], v[6:7] op_sel_hi:[0,1]
	v_lshl_add_u64 v[36:37], s[90:91], 0, v[112:113]
	v_cvt_pk_bf16_f32 v4, v4, v5
	v_cvt_pk_bf16_f32 v5, v6, v7
	global_store_dwordx2 v[36:37], v[4:5], off offset:-64
	v_pk_mul_f32 v[4:5], v[2:3], v[8:9] op_sel_hi:[0,1]
	v_pk_mul_f32 v[6:7], v[2:3], v[10:11] op_sel_hi:[0,1]
	v_cvt_pk_bf16_f32 v4, v4, v5
	v_cvt_pk_bf16_f32 v5, v6, v7
	global_store_dwordx2 v[36:37], v[4:5], off offset:-48
	v_pk_mul_f32 v[4:5], v[2:3], v[12:13] op_sel_hi:[0,1]
	v_pk_mul_f32 v[6:7], v[2:3], v[14:15] op_sel_hi:[0,1]
	v_cvt_pk_bf16_f32 v4, v4, v5
	v_cvt_pk_bf16_f32 v5, v6, v7
	global_store_dwordx2 v[36:37], v[4:5], off offset:-32
	v_pk_mul_f32 v[4:5], v[2:3], v[16:17] op_sel_hi:[0,1]
	v_pk_mul_f32 v[6:7], v[2:3], v[18:19] op_sel_hi:[0,1]
	v_cvt_pk_bf16_f32 v4, v4, v5
	v_cvt_pk_bf16_f32 v5, v6, v7
	global_store_dwordx2 v[36:37], v[4:5], off offset:-16
	v_pk_mul_f32 v[4:5], v[2:3], v[20:21] op_sel_hi:[0,1]
	v_pk_mul_f32 v[6:7], v[2:3], v[22:23] op_sel_hi:[0,1]
	v_cvt_pk_bf16_f32 v4, v4, v5
	v_cvt_pk_bf16_f32 v5, v6, v7
	global_store_dwordx2 v[36:37], v[4:5], off
	v_pk_mul_f32 v[4:5], v[2:3], v[24:25] op_sel_hi:[0,1]
	v_pk_mul_f32 v[6:7], v[2:3], v[26:27] op_sel_hi:[0,1]
	v_cvt_pk_bf16_f32 v4, v4, v5
	v_cvt_pk_bf16_f32 v5, v6, v7
	global_store_dwordx2 v[36:37], v[4:5], off offset:16
	v_pk_mul_f32 v[4:5], v[2:3], v[28:29] op_sel_hi:[0,1]
	v_pk_mul_f32 v[6:7], v[2:3], v[30:31] op_sel_hi:[0,1]
	v_cvt_pk_bf16_f32 v4, v4, v5
	v_cvt_pk_bf16_f32 v5, v6, v7
	global_store_dwordx2 v[36:37], v[4:5], off offset:32
	v_pk_mul_f32 v[4:5], v[2:3], v[32:33] op_sel_hi:[0,1]
	v_pk_mul_f32 v[6:7], v[2:3], v[34:35] op_sel_hi:[0,1]
	v_cvt_pk_bf16_f32 v4, v4, v5
	v_cvt_pk_bf16_f32 v5, v6, v7
	v_lshl_add_u64 v[112:113], v[112:113], 0, s[6:7]
	global_store_dwordx2 v[36:37], v[4:5], off offset:48
	s_cbranch_scc1 .LBB0_834
	s_add_i32 s14, s14, 32
	s_add_i32 s13, s13, 32
	s_bitcmp1_b32 s14, 5
	s_cbranch_scc1 .LBB0_829

.LBB0_887:
	v_readlane_b32 s2, v254, 18
	s_cmp_le_i32 s84, s2
	s_cselect_b64 s[0:1], -1, 0
	s_cmp_lt_i32 s2, s85
	s_cselect_b64 s[2:3], -1, 0
	s_and_b64 s[0:1], s[0:1], s[2:3]
	s_and_b64 vcc, exec, s[0:1]
	s_cbranch_vccz .LBB0_941
	v_readlane_b32 s4, v252, 4
	s_lshr_b32 s0, s83, 5
	s_lshl_b32 s0, s0, 11
	s_and_b32 s10, s83, 31
	s_lshl_b32 s10, s10, 3
	s_add_i32 s0, s0, s10
	s_add_i32 s10, s0, s4
	s_cmpk_gt_i32 s10, 0x3fff
	s_cbranch_scc1 .LBB0_891
	s_load_dwordx2 s[2:3], s[86:87], 0x188
	v_lshlrev_b32_e32 v24, 1, v196
	v_ashrrev_i32_e32 v25, 31, v24
	v_lshlrev_b64 v[40:41], 4, v[24:25]
	v_add_u32_e32 v16, 0x100, v24
	v_add_u32_e32 v24, 0x180, v24
	s_waitcnt lgkmcnt(0)
	v_lshl_add_u64 v[12:13], s[2:3], 0, v[40:41]
	v_ashrrev_i32_e32 v17, 31, v16
	v_ashrrev_i32_e32 v25, 31, v24
	global_load_dwordx4 v[0:3], v[12:13], off offset:16
	global_load_dwordx4 v[4:7], v[12:13], off
	global_load_dwordx4 v[8:11], v[12:13], off offset:2064
	s_nop 0
	global_load_dwordx4 v[12:15], v[12:13], off offset:2048
	v_lshlrev_b64 v[42:43], 4, v[16:17]
	v_lshlrev_b64 v[44:45], 4, v[24:25]
	v_lshl_add_u64 v[20:21], s[2:3], 0, v[42:43]
	v_lshl_add_u64 v[28:29], s[2:3], 0, v[44:45]
	global_load_dwordx4 v[16:19], v[20:21], off offset:16
	s_nop 0
	global_load_dwordx4 v[20:23], v[20:21], off
	s_nop 0
	global_load_dwordx4 v[24:27], v[28:29], off offset:16
	s_nop 0
	global_load_dwordx4 v[28:31], v[28:29], off
	v_and_b32_e32 v32, 64, v245
	v_add_u32_e32 v32, 64, v32
	v_xor_b32_e32 v33, 1, v245
	v_cmp_lt_i32_e32 vcc, v33, v32
	s_movk_i32 s2, 0x100
	s_ashr_i32 s1, s4, 31
	v_cndmask_b32_e32 v33, v245, v33, vcc
	v_lshlrev_b32_e32 v50, 2, v33
	v_xor_b32_e32 v33, 2, v245
	v_cmp_lt_i32_e32 vcc, v33, v32
	s_ashr_i32 s3, s0, 31
	s_add_u32 s0, s4, s0
	v_cndmask_b32_e32 v33, v245, v33, vcc
	v_lshlrev_b32_e32 v51, 2, v33
	v_xor_b32_e32 v33, 4, v245
	v_cmp_lt_i32_e32 vcc, v33, v32
	s_addc_u32 s1, s1, s3
	s_lshl_b64 s[4:5], s[0:1], 13
	v_cndmask_b32_e32 v33, v245, v33, vcc
	v_lshlrev_b32_e32 v52, 2, v33
	v_xor_b32_e32 v33, 8, v245
	v_cmp_lt_i32_e32 vcc, v33, v32
	v_readlane_b32 s6, v252, 2
	v_readlane_b32 s7, v252, 3
	v_cndmask_b32_e32 v33, v245, v33, vcc
	v_lshlrev_b32_e32 v53, 2, v33
	v_xor_b32_e32 v33, 16, v245
	v_cmp_lt_i32_e32 vcc, v33, v32
	s_add_u32 s4, s6, s4
	s_addc_u32 s5, s7, s5
	v_cndmask_b32_e32 v33, v245, v33, vcc
	s_ashr_i32 s3, s2, 31
	v_lshlrev_b32_e32 v54, 2, v33
	v_xor_b32_e32 v33, 32, v245
	s_lshl_b64 s[6:7], s[2:3], 13
	s_lshl_b64 s[0:1], s[0:1], 12
	v_cmp_lt_i32_e32 vcc, v33, v32
	s_add_u32 s0, s90, s0
	v_ashrrev_i32_e32 v197, 31, v196
	v_cndmask_b32_e32 v32, v245, v33, vcc
	s_addc_u32 s1, s91, s1
	v_lshlrev_b32_e32 v55, 2, v32
	v_lshl_add_u64 v[32:33], v[196:197], 4, s[0:1]
	s_mov_b64 s[0:1], 0x27300800
	v_or_b32_e32 v44, 16, v44
	v_or_b32_e32 v42, 16, v42
	v_lshl_add_u64 v[46:47], v[32:33], 0, s[0:1]
	s_lshl_b64 s[8:9], s[2:3], 12
	v_mov_b32_e32 v56, 0x3727c5ac
	s_mov_b32 s3, 0xf800000
	v_mov_b32_e32 v57, 0x260
.LBB0_890:
	global_load_dwordx4 v[32:35], v[46:47], off offset:-2048
	global_load_dwordx4 v[36:39], v[46:47], off offset:-1024
	global_load_dwordx4 v[58:61], v[46:47], off
	global_load_dwordx4 v[62:65], v[46:47], off offset:1024
	s_add_i32 s10, s10, s2
	v_lshl_add_u64 v[48:49], s[4:5], 0, v[40:41]
	v_lshl_add_u64 v[82:83], s[4:5], 0, v[42:43]
	v_lshl_add_u64 v[84:85], s[4:5], 0, v[44:45]
	s_add_u32 s4, s4, s6
	s_addc_u32 s5, s5, s7
	v_lshl_add_u64 v[46:47], v[46:47], 0, s[8:9]
	s_and_b32 s11, s10, 0x700
	s_waitcnt vmcnt(0)
	v_and_b32_e32 v67, 0xffff0000, v32
	v_lshlrev_b32_e32 v66, 16, v32
	v_mul_f32_e32 v88, v67, v67
	v_lshlrev_b32_e32 v32, 16, v33
	v_fmac_f32_e32 v88, v66, v66
	v_and_b32_e32 v33, 0xffff0000, v33
	v_fmac_f32_e32 v88, v32, v32
	v_lshlrev_b32_e32 v68, 16, v34
	v_fmac_f32_e32 v88, v33, v33
	v_and_b32_e32 v69, 0xffff0000, v34
	v_fmac_f32_e32 v88, v68, v68
	v_lshlrev_b32_e32 v34, 16, v35
	v_fmac_f32_e32 v88, v69, v69
	v_and_b32_e32 v35, 0xffff0000, v35
	v_fmac_f32_e32 v88, v34, v34
	v_lshlrev_b32_e32 v70, 16, v36
	v_fmac_f32_e32 v88, v35, v35
	v_and_b32_e32 v71, 0xffff0000, v36
	v_fmac_f32_e32 v88, v70, v70
	v_lshlrev_b32_e32 v36, 16, v37
	v_fmac_f32_e32 v88, v71, v71
	v_and_b32_e32 v37, 0xffff0000, v37
	v_fmac_f32_e32 v88, v36, v36
	v_lshlrev_b32_e32 v72, 16, v38
	v_fmac_f32_e32 v88, v37, v37
	v_and_b32_e32 v73, 0xffff0000, v38
	v_fmac_f32_e32 v88, v72, v72
	v_lshlrev_b32_e32 v38, 16, v39
	v_fmac_f32_e32 v88, v73, v73
	v_and_b32_e32 v39, 0xffff0000, v39
	v_fmac_f32_e32 v88, v38, v38
	v_lshlrev_b32_e32 v74, 16, v58
	v_fmac_f32_e32 v88, v39, v39
	v_and_b32_e32 v75, 0xffff0000, v58
	v_fmac_f32_e32 v88, v74, v74
	v_lshlrev_b32_e32 v58, 16, v59
	v_fmac_f32_e32 v88, v75, v75
	v_and_b32_e32 v59, 0xffff0000, v59
	v_fmac_f32_e32 v88, v58, v58
	v_lshlrev_b32_e32 v76, 16, v60
	v_fmac_f32_e32 v88, v59, v59
	v_and_b32_e32 v77, 0xffff0000, v60
	v_fmac_f32_e32 v88, v76, v76
	v_lshlrev_b32_e32 v60, 16, v61
	v_fmac_f32_e32 v88, v77, v77
	v_and_b32_e32 v61, 0xffff0000, v61
	v_fmac_f32_e32 v88, v60, v60
	v_lshlrev_b32_e32 v78, 16, v62
	v_fmac_f32_e32 v88, v61, v61
	v_and_b32_e32 v79, 0xffff0000, v62
	v_fmac_f32_e32 v88, v78, v78
	v_lshlrev_b32_e32 v62, 16, v63
	v_fmac_f32_e32 v88, v79, v79
	v_and_b32_e32 v63, 0xffff0000, v63
	v_fmac_f32_e32 v88, v62, v62
	v_lshlrev_b32_e32 v80, 16, v64
	v_fmac_f32_e32 v88, v63, v63
	v_and_b32_e32 v81, 0xffff0000, v64
	v_and_b32_e32 v64, 0xffff0000, v65
	v_lshlrev_b32_e32 v65, 16, v65
	v_fmac_f32_e32 v88, v80, v80
	v_pk_mul_f32 v[86:87], v[64:65], v[64:65]
	v_fmac_f32_e32 v88, v81, v81
	v_add_f32_e32 v87, v87, v88
	v_add_f32_e32 v86, v86, v87
	ds_bpermute_b32 v87, v50, v86
	s_waitcnt lgkmcnt(0)
	v_add_f32_e32 v86, v86, v87
	ds_bpermute_b32 v87, v51, v86
	s_waitcnt lgkmcnt(0)
	v_add_f32_e32 v86, v86, v87
	ds_bpermute_b32 v87, v52, v86
	s_waitcnt lgkmcnt(0)
	v_add_f32_e32 v86, v86, v87
	ds_bpermute_b32 v87, v53, v86
	s_waitcnt lgkmcnt(0)
	v_add_f32_e32 v86, v86, v87
	ds_bpermute_b32 v87, v54, v86
	s_waitcnt lgkmcnt(0)
	v_add_f32_e32 v86, v86, v87
	ds_bpermute_b32 v87, v55, v86
	s_waitcnt lgkmcnt(0)
	v_add_f32_e32 v86, v86, v87
	v_fmamk_f32 v86, v86, 0x3a000000, v56
	v_mul_f32_e32 v87, 0x4f800000, v86
	v_cmp_gt_f32_e32 vcc, s3, v86
	s_nop 1
	v_cndmask_b32_e32 v86, v86, v87, vcc
	v_sqrt_f32_e32 v87, v86
	s_nop 0
	v_add_u32_e32 v88, -1, v87
	v_add_u32_e32 v89, 1, v87
	v_fma_f32 v90, -v88, v87, v86
	v_fma_f32 v91, -v89, v87, v86
	v_cmp_ge_f32_e64 s[0:1], 0, v90
	s_nop 1
	v_cndmask_b32_e64 v87, v87, v88, s[0:1]
	v_cmp_lt_f32_e64 s[0:1], 0, v91
	s_nop 1
	v_cndmask_b32_e64 v87, v87, v89, s[0:1]
	v_mul_f32_e32 v88, 0x37800000, v87
	v_cndmask_b32_e32 v87, v87, v88, vcc
	v_cmp_class_f32_e32 vcc, v86, v57
	s_nop 1
	v_cndmask_b32_e32 v86, v87, v86, vcc
	v_div_scale_f32 v87, s[0:1], v86, v86, 1.0
	v_rcp_f32_e32 v89, v87
	v_div_scale_f32 v88, vcc, 1.0, v86, 1.0
	v_fma_f32 v90, -v87, v89, 1.0
	v_fmac_f32_e32 v89, v90, v89
	v_mul_f32_e32 v90, v88, v89
	v_fma_f32 v91, -v87, v90, v88
	v_fmac_f32_e32 v90, v91, v89
	v_fma_f32 v87, -v87, v90, v88
	v_div_fmas_f32 v87, v87, v89, v90
	v_div_fixup_f32 v86, v87, v86, 1.0
	v_pk_mul_f32 v[66:67], v[66:67], v[86:87] op_sel_hi:[1,0]
	v_pk_mul_f32 v[32:33], v[32:33], v[86:87] op_sel_hi:[1,0]
	v_pk_mul_f32 v[68:69], v[68:69], v[86:87] op_sel_hi:[1,0]
	v_pk_mul_f32 v[88:89], v[34:35], v[86:87] op_sel_hi:[1,0]
	v_pk_mul_f32 v[70:71], v[70:71], v[86:87] op_sel_hi:[1,0]
	v_pk_mul_f32 v[90:91], v[36:37], v[86:87] op_sel_hi:[1,0]
	v_pk_mul_f32 v[72:73], v[72:73], v[86:87] op_sel_hi:[1,0]
	v_pk_mul_f32 v[92:93], v[38:39], v[86:87] op_sel_hi:[1,0]
	v_pk_mul_f32 v[74:75], v[74:75], v[86:87] op_sel_hi:[1,0]
	v_pk_mul_f32 v[94:95], v[58:59], v[86:87] op_sel_hi:[1,0]
	v_pk_mul_f32 v[76:77], v[76:77], v[86:87] op_sel_hi:[1,0]
	v_pk_mul_f32 v[96:97], v[60:61], v[86:87] op_sel_hi:[1,0]
	v_pk_mul_f32 v[78:79], v[78:79], v[86:87] op_sel_hi:[1,0]
	v_pk_mul_f32 v[98:99], v[62:63], v[86:87] op_sel_hi:[1,0]
	v_pk_mul_f32 v[100:101], v[80:81], v[86:87] op_sel_hi:[1,0]
	v_pk_mul_f32 v[80:81], v[64:65], v[86:87] op_sel:[1,0] op_sel_hi:[0,0]
	v_pk_mul_f32 v[34:35], v[6:7], v[32:33]
	v_pk_mul_f32 v[32:33], v[4:5], v[66:67]
	v_pk_mul_f32 v[38:39], v[2:3], v[88:89]
	v_pk_mul_f32 v[36:37], v[0:1], v[68:69]
	v_pk_mul_f32 v[60:61], v[14:15], v[90:91]
	v_pk_mul_f32 v[58:59], v[12:13], v[70:71]
	v_pk_mul_f32 v[64:65], v[10:11], v[92:93]
	v_pk_mul_f32 v[62:63], v[8:9], v[72:73]
	v_pk_mul_f32 v[68:69], v[22:23], v[94:95]
	v_pk_mul_f32 v[66:67], v[20:21], v[74:75]
	v_pk_mul_f32 v[72:73], v[18:19], v[96:97]
	v_pk_mul_f32 v[70:71], v[16:17], v[76:77]
	v_pk_mul_f32 v[76:77], v[30:31], v[98:99]
	v_pk_mul_f32 v[74:75], v[28:29], v[78:79]
	v_pk_mul_f32 v[80:81], v[26:27], v[80:81]
	v_pk_mul_f32 v[78:79], v[24:25], v[100:101]
	global_store_dwordx4 v[48:49], v[32:35], off
	global_store_dwordx4 v[48:49], v[36:39], off offset:16
	global_store_dwordx4 v[48:49], v[58:61], off offset:2048
	global_store_dwordx4 v[48:49], v[62:65], off offset:2064
	global_store_dwordx4 v[82:83], v[66:69], off offset:-16
	global_store_dwordx4 v[82:83], v[70:73], off
	global_store_dwordx4 v[84:85], v[74:77], off offset:-16
	global_store_dwordx4 v[84:85], v[78:81], off
	s_cbranch_scc1 .LBB0_890
